# v9 plus exact counted vmcnt at V staging writes and single compare per loop guard
# baseline (speedup 1.0000x reference)
; template <int DQK, int MODE, bool PIPE>
; DI void attn_core(const u16* __restrict__ Qg, const u16* __restrict__ Kg, const u16* __restrict__ Vtg, int ntiles,
;                   int kr_lo, int rs, int r_q, int c_q, int cs, const float* biasL, char* lds, f32x16 (&o)[4], float& l_out, int tid) {
;     ...
;   auto gloadV = [&](int t) {
;     const int key0 = keystart(t);
; #pragma unroll
;     for (int j = 0; j < 2; ++j) { const int q = tid + NT_ * j; rv[j] = *(const u32x4*)(Vtg + (size_t)(q >> 3) * NR + key0 + (q & 7) * 8); }
;   };
;   auto swriteK = [&](int b) {
;     char* base = lds + b * A_BUF;
; #pragma unroll
;     for (int j = 0; j < KPT; ++j) { const int q = tid + NT_ * j; const int row = q / NKP, pcs = q - row * NKP;
;       *(u32x4*)(base + row * KSTR + pcs * 16) = rk[j]; }
;   };
;   auto swriteV = [&](int b) {
;     char* base = lds + b * A_BUF;
; #pragma unroll
;     for (int j = 0; j < 2; ++j) { const int q = tid + NT_ * j; char* d = base + A_VOFF + (q >> 3) * 136 + (q & 7) * 16;
;       u32x2 lo = {rv[j][0], rv[j][1]}, hi = {rv[j][2], rv[j][3]};
;       *(u32x2*)d = lo; *(u32x2*)(d + 8) = hi; }
;   };
;     ...
;   auto step = [&](int t, f32x16& c0, f32x16& c1, f32x16& n0, f32x16& n1) {
;     if (t + 1 < ntiles) swriteV((t + 1) & 1);
;     if (t + 2 < ntiles) gloadV(t + 2);
.LBB0_817:
	s_add_i32 s18, s6, 1
	s_cmp_lt_u32 s18, s17
	s_cselect_b64 s[10:11], -1, 0
	s_cbranch_scc0 .LBB0_819
	s_bitcmp1_b32 s18, 0
	s_cselect_b32 s7, 0xa800, 0
	v_add_u32_e32 v66, s7, v223
	v_add3_u32 v66, v66, v166, s33
	v_add_u32_e32 v67, s7, v224
	v_add3_u32 v67, v67, v166, s33
	s_waitcnt vmcnt(4)
	ds_write2_b64 v66, v[150:151], v[152:153] offset1:1
	s_waitcnt vmcnt(3)
	ds_write2_b64 v67, v[158:159], v[160:161] offset1:1
.LBB0_819:
	s_add_i32 s7, s6, 2
	s_cmp_lt_u32 s7, s17
	s_cselect_b64 s[14:15], -1, 0
	s_cbranch_scc0 .LBB0_821
	global_load_dwordx4 v[150:153], v[176:177], off
	global_load_dwordx4 v[158:161], v[218:219], off

; template <int DQK, int MODE, bool PIPE>
; DI void attn_core(const u16* __restrict__ Qg, const u16* __restrict__ Kg, const u16* __restrict__ Vtg, int ntiles,
;                   int kr_lo, int rs, int r_q, int c_q, int cs, const float* biasL, char* lds, f32x16 (&o)[4], float& l_out, int tid) {
;     ...
;   auto gloadV = [&](int t) {
;     const int key0 = keystart(t);
; #pragma unroll
;     for (int j = 0; j < 2; ++j) { const int q = tid + NT_ * j; rv[j] = *(const u32x4*)(Vtg + (size_t)(q >> 3) * NR + key0 + (q & 7) * 8); }
;   };
;   auto swriteK = [&](int b) {
;     char* base = lds + b * A_BUF;
; #pragma unroll
;     for (int j = 0; j < KPT; ++j) { const int q = tid + NT_ * j; const int row = q / NKP, pcs = q - row * NKP;
;       *(u32x4*)(base + row * KSTR + pcs * 16) = rk[j]; }
;   };
;   auto swriteV = [&](int b) {
;     char* base = lds + b * A_BUF;
; #pragma unroll
;     for (int j = 0; j < 2; ++j) { const int q = tid + NT_ * j; char* d = base + A_VOFF + (q >> 3) * 136 + (q & 7) * 16;
;       u32x2 lo = {rv[j][0], rv[j][1]}, hi = {rv[j][2], rv[j][3]};
;       *(u32x2*)d = lo; *(u32x2*)(d + 8) = hi; }
;   };
;     ...
;   auto step = [&](int t, f32x16& c0, f32x16& c1, f32x16& n0, f32x16& n1) {
;     if (t + 1 < ntiles) swriteV((t + 1) & 1);
;     if (t + 2 < ntiles) gloadV(t + 2);
.LBB0_838:
	s_add_i32 s14, s15, 1
	s_cmp_lt_u32 s14, s10
	s_cselect_b64 s[0:1], -1, 0
	s_cbranch_scc0 .LBB0_840
	s_bitcmp1_b32 s14, 0
	s_cselect_b32 s6, 0xa800, 0
	v_add_u32_e32 v82, s6, v164
	v_add3_u32 v82, v82, v142, s33
	v_add_u32_e32 v83, s6, v165
	v_add3_u32 v83, v83, v142, s33
	s_waitcnt vmcnt(2)
	ds_write2_b64 v82, v[130:131], v[132:133] offset1:1
	s_waitcnt vmcnt(1)
	ds_write2_b64 v83, v[134:135], v[136:137] offset1:1
.LBB0_840:
	s_add_i32 s16, s15, 2
	s_cmp_lt_u32 s16, s10
	s_cselect_b64 s[6:7], -1, 0
	s_cbranch_scc0 .LBB0_842
	global_load_dwordx4 v[130:133], v[162:163], off
	global_load_dwordx4 v[134:137], v[150:151], off

; template <int DQK, int MODE, bool PIPE>
; DI void attn_core(const u16* __restrict__ Qg, const u16* __restrict__ Kg, const u16* __restrict__ Vtg, int ntiles,
;                   int kr_lo, int rs, int r_q, int c_q, int cs, const float* biasL, char* lds, f32x16 (&o)[4], float& l_out, int tid) {
;     ...
;   auto gloadV = [&](int t) {
;     const int key0 = keystart(t);
; #pragma unroll
;     for (int j = 0; j < 2; ++j) { const int q = tid + NT_ * j; rv[j] = *(const u32x4*)(Vtg + (size_t)(q >> 3) * NR + key0 + (q & 7) * 8); }
;   };
;   auto swriteK = [&](int b) {
;     char* base = lds + b * A_BUF;
; #pragma unroll
;     for (int j = 0; j < KPT; ++j) { const int q = tid + NT_ * j; const int row = q / NKP, pcs = q - row * NKP;
;       *(u32x4*)(base + row * KSTR + pcs * 16) = rk[j]; }
;   };
;   auto swriteV = [&](int b) {
;     char* base = lds + b * A_BUF;
; #pragma unroll
;     for (int j = 0; j < 2; ++j) { const int q = tid + NT_ * j; char* d = base + A_VOFF + (q >> 3) * 136 + (q & 7) * 16;
;       u32x2 lo = {rv[j][0], rv[j][1]}, hi = {rv[j][2], rv[j][3]};
;       *(u32x2*)d = lo; *(u32x2*)(d + 8) = hi; }
;   };
;     ...
;   auto step = [&](int t, f32x16& c0, f32x16& c1, f32x16& n0, f32x16& n1) {
;     if (t + 1 < ntiles) swriteV((t + 1) & 1);
;     if (t + 2 < ntiles) gloadV(t + 2);
.LBB0_854:
	s_add_i32 s11, s12, 1
	s_cmp_lt_u32 s11, s10
	s_cselect_b64 s[0:1], -1, 0
	s_cbranch_scc0 .LBB0_856
	s_bitcmp1_b32 s11, 0
	s_cselect_b32 s6, 0xa800, 0
	v_add_u32_e32 v82, s6, v164
	v_add3_u32 v82, v82, v142, s33
	v_add_u32_e32 v83, s6, v165
	v_add3_u32 v83, v83, v142, s33
	s_waitcnt vmcnt(2)
	ds_write2_b64 v82, v[130:131], v[132:133] offset1:1
	s_waitcnt vmcnt(1)
	ds_write2_b64 v83, v[134:135], v[136:137] offset1:1
.LBB0_856:
	s_add_i32 s14, s12, 2
	s_cmp_lt_u32 s14, s10
	s_cselect_b64 s[6:7], -1, 0
	s_cbranch_scc0 .LBB0_858
	global_load_dwordx4 v[130:133], v[146:147], off
	global_load_dwordx4 v[134:137], v[148:149], off
